# in-proj GEMM: context-row tiles outside the kv columns (no output) are not computed
# baseline (speedup 1.0000x reference)
.LBB0_164:
	s_cmp_lt_u32 s88, 64
	s_cbranch_scc1 .Lp2_keep
	s_sub_u32 s101, s86, 12
	s_cmp_lt_u32 s101, 3
	s_cbranch_scc1 .Lp2_keep
	s_mov_b64 s[0:1], 0
